# adds counted waits in d3_qlat/d5_oproj block loops (result stores stay in flight)
# baseline (speedup 1.0000x reference)
.LBB0_1334:
	s_and_b32 s8, s10, 15
	s_lshl_b32 s6, s8, 9
	s_waitcnt vmcnt(16)
	v_lshl_add_u64 v[2:3], v[78:79], 0, s[6:7]
	s_waitcnt vmcnt(4)
	v_lshlrev_b64 v[50:51], 8, v[2:3]
	s_ashr_i32 s9, s10, 4
	v_lshl_add_u64 v[18:19], v[74:75], 0, v[50:51]
	s_lshl_b32 s13, s9, 6
	global_load_dwordx4 v[2:5], v[18:19], off
	global_load_dwordx4 v[6:9], v[18:19], off offset:64
	global_load_dwordx4 v[10:13], v[18:19], off offset:128
	global_load_dwordx4 v[14:17], v[18:19], off offset:192
	v_or_b32_e32 v18, 0x400, v50
	v_mov_b32_e32 v19, v51
	s_add_i32 s11, s13, 64
	v_lshl_add_u64 v[34:35], v[74:75], 0, v[18:19]
	global_load_dwordx4 v[18:21], v[34:35], off
	global_load_dwordx4 v[22:25], v[34:35], off offset:64
	global_load_dwordx4 v[26:29], v[34:35], off offset:128
	global_load_dwordx4 v[30:33], v[34:35], off offset:192
	v_or_b32_e32 v34, 0x2000, v50
	v_mov_b32_e32 v35, v51
	v_or_b32_e32 v50, 0x2400, v50
	s_cmp_lg_u32 s9, 15
	v_lshl_add_u64 v[52:53], v[74:75], 0, v[34:35]
	s_waitcnt vmcnt(8)
	v_lshl_add_u64 v[66:67], v[74:75], 0, v[50:51]
	s_cselect_b32 s11, s11, 0x401
	s_lshl_b32 s12, s9, 10
	global_load_dwordx4 v[34:37], v[52:53], off
	global_load_dwordx4 v[38:41], v[52:53], off offset:64
	global_load_dwordx4 v[42:45], v[52:53], off offset:128
	global_load_dwordx4 v[46:49], v[52:53], off offset:192
	s_nop 0
	global_load_dwordx4 v[50:53], v[66:67], off
	global_load_dwordx4 v[54:57], v[66:67], off offset:64
	global_load_dwordx4 v[58:61], v[66:67], off offset:128
	global_load_dwordx4 v[62:65], v[66:67], off offset:192
	v_or_b32_e32 v66, s12, v84
	v_mad_i64_i32 v[66:67], s[14:15], v66, s3, v[80:81]
	s_lshl_b32 s14, s8, 8
	s_mov_b32 s15, s7
	v_lshl_add_u64 v[66:67], v[66:67], 0, s[14:15]
	v_lshl_add_u64 v[66:67], v[66:67], 0, v[72:73]
	v_add_co_u32_e32 v66, vcc, 0x3000, v66
	s_cmp_ge_i32 s13, s11
	s_nop 0
	v_addc_co_u32_e32 v67, vcc, 0, v67, vcc
	global_load_dwordx4 v[66:69], v[66:67], off offset:896
	s_barrier
	s_cbranch_scc1 .LBB0_1333
	s_waitcnt vmcnt(0)
	s_lshl_b32 s8, s8, 7
	s_lshl_b32 s6, s6, 1
	v_lshl_add_u64 v[82:83], v[76:77], 0, s[6:7]
	s_lshl_b32 s6, s8, 1
	s_branch .LBB0_1337
.LBB0_1336:
	s_or_b64 exec, exec, s[8:9]
	s_add_i32 s15, s13, 1
	s_cmp_lt_i32 s15, s11
	s_cselect_b32 s8, s15, s13
	s_waitcnt vmcnt(2)
	v_lshl_or_b32 v68, s8, 4, v84
	v_mov_b64_e32 v[66:67], s[0:1]
	v_mad_i64_i32 v[66:67], s[8:9], v68, s3, v[66:67]
	v_lshl_add_u64 v[66:67], v[66:67], 0, s[6:7]
	v_lshl_add_u64 v[66:67], v[66:67], 0, v[72:73]
	v_add_co_u32_e32 v66, vcc, 0x3000, v66
	v_add3_u32 v106, s14, v85, v70
	s_nop 0
	v_addc_co_u32_e32 v67, vcc, 0, v67, vcc
	global_load_dwordx4 v[66:69], v[66:67], off offset:896
	s_waitcnt lgkmcnt(0)
	s_barrier
	ds_read_b128 v[86:89], v106
	ds_read_b128 v[90:93], v106 offset:64
	s_waitcnt lgkmcnt(1)
	v_mfma_f32_16x16x32_bf16 v[94:97], v[2:5], v[86:89], 0
	ds_read_b128 v[102:105], v106 offset:128
	ds_read_b128 v[106:109], v106 offset:192
	v_add_u32_e32 v114, s12, v1
	v_ashrrev_i32_e32 v115, 31, v114
	v_mfma_f32_16x16x32_bf16 v[98:101], v[18:21], v[86:89], 0
	s_add_i32 s8, s12, 16
	s_cmp_ge_i32 s15, s11
	s_mov_b32 s12, s8
	v_mfma_f32_16x16x32_bf16 v[110:113], v[34:37], v[86:89], 0
	s_mov_b32 s13, s15
	v_mfma_f32_16x16x32_bf16 v[86:89], v[50:53], v[86:89], 0
	s_waitcnt lgkmcnt(2)
	v_mfma_f32_16x16x32_bf16 v[94:97], v[6:9], v[90:93], v[94:97]
	v_mfma_f32_16x16x32_bf16 v[98:101], v[22:25], v[90:93], v[98:101]
	v_mfma_f32_16x16x32_bf16 v[110:113], v[38:41], v[90:93], v[110:113]
	v_mfma_f32_16x16x32_bf16 v[86:89], v[54:57], v[90:93], v[86:89]
	s_waitcnt lgkmcnt(1)
	v_mfma_f32_16x16x32_bf16 v[94:97], v[10:13], v[102:105], v[94:97]
	v_mfma_f32_16x16x32_bf16 v[98:101], v[26:29], v[102:105], v[98:101]
	v_mfma_f32_16x16x32_bf16 v[90:93], v[42:45], v[102:105], v[110:113]
	v_mfma_f32_16x16x32_bf16 v[86:89], v[58:61], v[102:105], v[86:89]
	s_nop 1
	v_lshlrev_b64 v[110:111], 14, v[114:115]
	v_lshl_add_u64 v[110:111], v[82:83], 0, v[110:111]
	s_waitcnt lgkmcnt(0)
	v_mfma_f32_16x16x32_bf16 v[94:97], v[14:17], v[106:109], v[94:97]
	v_mfma_f32_16x16x32_bf16 v[98:101], v[30:33], v[106:109], v[98:101]
	v_mfma_f32_16x16x32_bf16 v[90:93], v[46:49], v[106:109], v[90:93]
	s_nop 5
	v_cvt_pk_bf16_f32 v94, v94, v95
	v_cvt_pk_bf16_f32 v95, v96, v97
	v_cvt_pk_bf16_f32 v96, v98, v99
	v_mfma_f32_16x16x32_bf16 v[86:89], v[62:65], v[106:109], v[86:89]
	v_cvt_pk_bf16_f32 v97, v100, v101
	v_cvt_pk_bf16_f32 v90, v90, v91
	v_cvt_pk_bf16_f32 v91, v92, v93
	global_store_dwordx4 v[110:111], v[94:97], off
	s_nop 3
	v_cvt_pk_bf16_f32 v92, v86, v87
	v_cvt_pk_bf16_f32 v93, v88, v89
	global_store_dwordx4 v[110:111], v[90:93], off offset:64
	s_cbranch_scc1 .LBB0_1333

.LBB0_1466:
	s_and_b32 s10, s3, 15
	s_lshl_b32 s9, s10, 7
	v_add_u32_e32 v76, s9, v75
	s_waitcnt vmcnt(17)
	v_lshlrev_b64 v[2:3], 10, v[76:77]
	s_waitcnt vmcnt(2)
	v_lshl_add_u64 v[62:63], v[78:79], 0, v[2:3]
	global_load_dwordx4 v[2:5], v[62:63], off
	global_load_dwordx4 v[6:9], v[62:63], off offset:64
	global_load_dwordx4 v[10:13], v[62:63], off offset:128
	global_load_dwordx4 v[14:17], v[62:63], off offset:192
	global_load_dwordx4 v[18:21], v[62:63], off offset:256
	global_load_dwordx4 v[22:25], v[62:63], off offset:320
	global_load_dwordx4 v[26:29], v[62:63], off offset:384
	global_load_dwordx4 v[30:33], v[62:63], off offset:448
	global_load_dwordx4 v[34:37], v[62:63], off offset:512
	global_load_dwordx4 v[38:41], v[62:63], off offset:576
	global_load_dwordx4 v[42:45], v[62:63], off offset:640
	global_load_dwordx4 v[46:49], v[62:63], off offset:704
	global_load_dwordx4 v[50:53], v[62:63], off offset:768
	global_load_dwordx4 v[54:57], v[62:63], off offset:832
	global_load_dwordx4 v[58:61], v[62:63], off offset:896
	s_nop 0
	global_load_dwordx4 v[62:65], v[62:63], off offset:960
	s_ashr_i32 s4, s3, 4
	s_lshl_b32 s8, s4, 6
	s_add_i32 s6, s8, 64
	s_cmp_lg_u32 s4, 15
	s_cselect_b32 s6, s6, 0x401
	s_lshl_b32 s7, s4, 10
	s_waitcnt vmcnt(17)
	v_or_b32_e32 v66, s7, v1
	v_ashrrev_i32_e32 v67, 31, v66
	v_lshlrev_b64 v[66:67], 14, v[66:67]
	v_lshl_add_u64 v[66:67], s[0:1], 0, v[66:67]
	s_lshl_b32 s4, s10, 10
	v_lshl_add_u64 v[66:67], v[66:67], 0, s[4:5]
	v_lshl_add_u64 v[86:87], v[66:67], 0, v[84:85]
	global_load_dwordx4 v[66:69], v[86:87], off
	global_load_dwordx4 v[70:73], v[86:87], off offset:512
	s_cmp_ge_i32 s8, s6
	s_barrier
	s_cbranch_scc1 .LBB0_1465
	s_waitcnt vmcnt(0)
	s_lshl_b32 s4, s10, 9
	s_lshl_b32 s4, s4, 1
	v_lshl_add_u64 v[86:87], v[80:81], 0, s[4:5]
	s_lshl_b32 s4, s9, 1
	v_lshl_add_u64 v[88:89], v[82:83], 0, s[4:5]
.LBB0_1468:
	s_and_b32 s4, s7, 16
	s_mulk_i32 s4, 0x410
	s_add_i32 s9, s8, 1
	s_add_i32 s4, s4, 0
	v_lshlrev_b32_e32 v76, 1, v74
	s_cmp_lt_i32 s9, s6
	v_add3_u32 v93, s4, v91, v84
	v_add3_u32 v76, s4, v92, v76
	s_cselect_b32 s4, s9, s8
	s_waitcnt vmcnt(1)
	ds_write_b128 v93, v[66:69]
	s_waitcnt vmcnt(1)
	ds_write_b128 v93, v[70:73] offset:512
	v_lshl_or_b32 v66, s4, 4, v1
	v_ashrrev_i32_e32 v67, 31, v66
	v_lshlrev_b64 v[66:67], 14, v[66:67]
	v_lshl_add_u64 v[94:95], v[86:87], 0, v[66:67]
	global_load_dwordx4 v[66:69], v[94:95], off
	global_load_dwordx4 v[70:73], v[94:95], off offset:512
	s_waitcnt lgkmcnt(0)
	s_barrier
	ds_read_b128 v[94:97], v76
	ds_read_b128 v[98:101], v76 offset:64
	ds_read_b128 v[102:105], v76 offset:128
	ds_read_b128 v[106:109], v76 offset:192
	s_waitcnt lgkmcnt(3)
	v_mfma_f32_16x16x32_bf16 v[94:97], v[2:5], v[94:97], 0
	v_add_u32_e32 v110, s7, v90
	v_ashrrev_i32_e32 v111, 31, v110
	s_add_i32 s7, s7, 16
	s_waitcnt lgkmcnt(2)
	v_mfma_f32_16x16x32_bf16 v[98:101], v[6:9], v[98:101], 0
	s_mov_b32 s8, s9
	s_cmp_ge_i32 s9, s6
	s_waitcnt lgkmcnt(1)
	v_mfma_f32_16x16x32_bf16 v[94:97], v[10:13], v[102:105], v[94:97]
	s_waitcnt lgkmcnt(0)
	v_mfma_f32_16x16x32_bf16 v[98:101], v[14:17], v[106:109], v[98:101]
	ds_read_b128 v[102:105], v76 offset:256
	ds_read_b128 v[106:109], v76 offset:320
	s_waitcnt lgkmcnt(1)
	v_mfma_f32_16x16x32_bf16 v[94:97], v[18:21], v[102:105], v[94:97]
	s_waitcnt lgkmcnt(0)
	v_mfma_f32_16x16x32_bf16 v[98:101], v[22:25], v[106:109], v[98:101]
	ds_read_b128 v[102:105], v76 offset:384
	ds_read_b128 v[106:109], v76 offset:448
	s_waitcnt lgkmcnt(1)
	v_mfma_f32_16x16x32_bf16 v[94:97], v[26:29], v[102:105], v[94:97]
	s_waitcnt lgkmcnt(0)
	v_mfma_f32_16x16x32_bf16 v[98:101], v[30:33], v[106:109], v[98:101]
	ds_read_b128 v[102:105], v76 offset:512
	ds_read_b128 v[106:109], v76 offset:576
	s_waitcnt lgkmcnt(1)
	v_mfma_f32_16x16x32_bf16 v[94:97], v[34:37], v[102:105], v[94:97]
	s_waitcnt lgkmcnt(0)
	v_mfma_f32_16x16x32_bf16 v[98:101], v[38:41], v[106:109], v[98:101]
	ds_read_b128 v[102:105], v76 offset:640
	ds_read_b128 v[106:109], v76 offset:704
	s_waitcnt lgkmcnt(1)
	v_mfma_f32_16x16x32_bf16 v[94:97], v[42:45], v[102:105], v[94:97]
	s_waitcnt lgkmcnt(0)
	v_mfma_f32_16x16x32_bf16 v[98:101], v[46:49], v[106:109], v[98:101]
	ds_read_b128 v[102:105], v76 offset:768
	ds_read_b128 v[106:109], v76 offset:832
	s_waitcnt lgkmcnt(1)
	v_mfma_f32_16x16x32_bf16 v[94:97], v[50:53], v[102:105], v[94:97]
	v_lshlrev_b64 v[102:103], 12, v[110:111]
	v_lshl_add_u64 v[110:111], v[88:89], 0, v[102:103]
	s_waitcnt lgkmcnt(0)
	v_mfma_f32_16x16x32_bf16 v[98:101], v[54:57], v[106:109], v[98:101]
	ds_read_b128 v[102:105], v76 offset:896
	ds_read_b128 v[106:109], v76 offset:960
	s_waitcnt lgkmcnt(1)
	v_mfma_f32_16x16x32_bf16 v[94:97], v[58:61], v[102:105], v[94:97]
	s_waitcnt lgkmcnt(0)
	v_mfma_f32_16x16x32_bf16 v[98:101], v[62:65], v[106:109], v[98:101]
	s_nop 7
	v_pk_add_f32 v[96:97], v[96:97], v[100:101]
	v_pk_add_f32 v[94:95], v[94:95], v[98:99]
	s_nop 0
	v_cvt_pk_bf16_f32 v94, v94, v95
	v_cvt_pk_bf16_f32 v95, v96, v97
	global_store_dwordx2 v[110:111], v[94:95], off
	s_cbranch_scc0 .LBB0_1468
	s_branch .LBB0_1465
